# NSA pass 2: dropped lgkmcnt waits that only guarded the removed bpermute results (the LDS importance atomics no longer serialize)
# speedup vs baseline: 1.0133x; 1.0028x over previous
.LBB0_1576:
	v_add_u32_e32 v14, s0, v11
	v_add_u32_e32 v15, v14, v0
	ds_read_b128 v[80:83], v15
	ds_read_b128 v[84:87], v15 offset:32
	v_add_u32_e32 v14, 0xfffffe00, v13
	v_cmp_le_i32_e64 s[0:1], v14, v188
	s_waitcnt lgkmcnt(1)
	v_mfma_f32_32x32x16_bf16 v[64:79], v[80:83], v[144:147], v[48:63]
	ds_read_b128 v[80:83], v15 offset:64
	s_waitcnt lgkmcnt(1)
	v_mfma_f32_32x32x16_bf16 v[64:79], v[84:87], v[148:151], v[64:79]
	s_waitcnt lgkmcnt(0)
	v_mfma_f32_32x32x16_bf16 v[64:79], v[80:83], v[152:155], v[64:79]
	ds_read_b128 v[80:83], v15 offset:96
	s_waitcnt lgkmcnt(0)
	v_mfma_f32_32x32x16_bf16 v[64:79], v[80:83], v[156:159], v[64:79]
	s_nop 11
	v_exp_f32_e32 v64, v64
	v_exp_f32_e32 v65, v65
	v_exp_f32_e32 v66, v66
	v_exp_f32_e32 v67, v67
	v_mul_f32_e32 v64, v190, v64
	v_cndmask_b32_e64 v14, 0, v64, s[0:1]
	v_add_u32_e32 v64, 0xfffffe10, v13
	v_mul_f32_e32 v65, v190, v65
	v_cmp_le_i32_e64 s[0:1], v64, v188
	v_mul_f32_e32 v66, v190, v66
	v_mul_f32_e32 v67, v190, v67
	v_cndmask_b32_e64 v64, 0, v65, s[0:1]
	v_add_u32_e32 v65, 0xfffffe20, v13
	v_cmp_le_i32_e64 s[0:1], v65, v188
	v_add_f32_e32 v14, v14, v64
	s_nop 0
	v_cndmask_b32_e64 v65, 0, v66, s[0:1]
	v_add_u32_e32 v66, 0xfffffe30, v13
	v_cmp_le_i32_e64 s[0:1], v66, v188
	s_nop 1
	v_cndmask_b32_e64 v66, 0, v67, s[0:1]
	v_add_f32_e32 v64, v65, v66
	v_add_f32_e32 v14, v14, v64
	s_nop 0
	s_nop 1
	v_mov_b32_dpp v64, v14 quad_perm:[1,0,3,2] row_mask:0xf bank_mask:0xf
	v_add_f32_e32 v64, v14, v64
	s_nop 0
	s_nop 1
	v_mov_b32_dpp v65, v64 quad_perm:[2,3,0,1] row_mask:0xf bank_mask:0xf
	s_nop 0
	s_nop 1
	v_mov_b32_dpp v14, v66 quad_perm:[1,0,3,2] row_mask:0xf bank_mask:0xf
	v_add_f32_e32 v66, v66, v14
	s_nop 0
	s_nop 1
	v_mov_b32_dpp v67, v66 quad_perm:[2,3,0,1] row_mask:0xf bank_mask:0xf
	v_add_u32_e32 v14, s4, v191
	s_and_saveexec_b64 s[2:3], vcc
	s_cbranch_execz .LBB0_1581
	s_cmpk_gt_u32 s4, 0x7f
	s_cbranch_scc1 .LBB0_1579
	v_add_f32_e32 v64, v64, v65
	ds_add_f32 v12, v64
.LBB0_1579:
	v_cmp_gt_u32_e64 s[0:1], s7, v14
	s_and_b64 exec, exec, s[0:1]
	s_cbranch_execz .LBB0_1581
	v_add_f32_e32 v64, v66, v67
	ds_add_f32 v12, v64 offset:4
.LBB0_1581:
	s_or_b64 exec, exec, s[2:3]
	v_exp_f32_e32 v64, v68
	v_exp_f32_e32 v66, v69
	v_add_u32_e32 v65, 0xfffffe80, v13
	v_exp_f32_e32 v67, v70
	v_mul_f32_e32 v64, v190, v64
	v_cmp_le_i32_e64 s[0:1], v65, v188
	v_add_u32_e32 v65, 0xfffffe90, v13
	v_mul_f32_e32 v66, v190, v66
	v_cndmask_b32_e64 v64, 0, v64, s[0:1]
	v_cmp_le_i32_e64 s[0:1], v65, v188
	v_exp_f32_e32 v68, v71
	v_mul_f32_e32 v67, v190, v67
	v_cndmask_b32_e64 v65, 0, v66, s[0:1]
	v_add_u32_e32 v66, 0xfffffea0, v13
	v_cmp_le_i32_e64 s[0:1], v66, v188
	v_mul_f32_e32 v68, v190, v68
	v_add_f32_e32 v64, v64, v65
	v_cndmask_b32_e64 v66, 0, v67, s[0:1]
	v_add_u32_e32 v67, 0xfffffeb0, v13
	v_cmp_le_i32_e64 s[0:1], v67, v188
	s_nop 1
	v_cndmask_b32_e64 v68, 0, v68, s[0:1]
	v_add_f32_e32 v65, v66, v68
	v_add_f32_e32 v64, v64, v65
	s_nop 1
	v_mov_b32_dpp v65, v64 quad_perm:[1,0,3,2] row_mask:0xf bank_mask:0xf
	v_add_f32_e32 v64, v64, v65
	s_nop 0
	s_nop 1
	v_mov_b32_dpp v66, v68 quad_perm:[1,0,3,2] row_mask:0xf bank_mask:0xf
	s_nop 1
	v_mov_b32_dpp v67, v64 quad_perm:[2,3,0,1] row_mask:0xf bank_mask:0xf
	v_add_f32_e32 v65, v68, v66
	s_nop 0
	s_nop 1
	v_mov_b32_dpp v66, v65 quad_perm:[2,3,0,1] row_mask:0xf bank_mask:0xf
	s_and_saveexec_b64 s[2:3], vcc
	s_cbranch_execz .LBB0_1586
	s_cmpk_gt_u32 s4, 0x7f
	s_cbranch_scc1 .LBB0_1584
	v_add_f32_e32 v64, v64, v67
	ds_add_f32 v12, v64 offset:8
.LBB0_1584:
	v_add_u32_e32 v64, 2, v14
	v_cmp_gt_u32_e64 s[0:1], s7, v64
	s_and_b64 exec, exec, s[0:1]
	s_cbranch_execz .LBB0_1586
	v_add_f32_e32 v64, v65, v66
	ds_add_f32 v12, v64 offset:12
.LBB0_1586:
	s_or_b64 exec, exec, s[2:3]
	v_exp_f32_e32 v64, v72
	v_exp_f32_e32 v66, v73
	v_add_u32_e32 v65, 0xffffff00, v13
	v_exp_f32_e32 v67, v74
	v_mul_f32_e32 v64, v190, v64
	v_cmp_le_i32_e64 s[0:1], v65, v188
	v_add_u32_e32 v65, 0xffffff10, v13
	v_mul_f32_e32 v66, v190, v66
	v_cndmask_b32_e64 v64, 0, v64, s[0:1]
	v_cmp_le_i32_e64 s[0:1], v65, v188
	v_exp_f32_e32 v68, v75
	v_mul_f32_e32 v67, v190, v67
	v_cndmask_b32_e64 v65, 0, v66, s[0:1]
	v_add_u32_e32 v66, 0xffffff20, v13
	v_cmp_le_i32_e64 s[0:1], v66, v188
	v_mul_f32_e32 v68, v190, v68
	v_add_f32_e32 v64, v64, v65
	v_cndmask_b32_e64 v66, 0, v67, s[0:1]
	v_add_u32_e32 v67, 0xffffff30, v13
	v_cmp_le_i32_e64 s[0:1], v67, v188
	s_nop 1
	v_cndmask_b32_e64 v68, 0, v68, s[0:1]
	v_add_f32_e32 v65, v66, v68
	v_add_f32_e32 v64, v64, v65
	s_nop 1
	v_mov_b32_dpp v65, v64 quad_perm:[1,0,3,2] row_mask:0xf bank_mask:0xf
	v_add_f32_e32 v64, v64, v65
	s_nop 0
	s_nop 1
	v_mov_b32_dpp v66, v68 quad_perm:[1,0,3,2] row_mask:0xf bank_mask:0xf
	s_nop 1
	v_mov_b32_dpp v67, v64 quad_perm:[2,3,0,1] row_mask:0xf bank_mask:0xf
	v_add_f32_e32 v65, v68, v66
	s_nop 0
	s_nop 1
	v_mov_b32_dpp v66, v65 quad_perm:[2,3,0,1] row_mask:0xf bank_mask:0xf
	s_and_saveexec_b64 s[2:3], vcc
	s_cbranch_execz .LBB0_1591
	s_cmpk_gt_u32 s4, 0x7f
	s_cbranch_scc1 .LBB0_1589
	v_add_f32_e32 v64, v64, v67
	ds_add_f32 v12, v64 offset:16
.LBB0_1589:
	v_add_u32_e32 v64, 4, v14
	v_cmp_gt_u32_e64 s[0:1], s7, v64
	s_and_b64 exec, exec, s[0:1]
	s_cbranch_execz .LBB0_1591
	v_add_f32_e32 v64, v65, v66
	ds_add_f32 v12, v64 offset:20
.LBB0_1591:
	s_or_b64 exec, exec, s[2:3]
	v_exp_f32_e32 v64, v76
	v_exp_f32_e32 v66, v77
	v_add_u32_e32 v65, 0xffffff80, v13
	v_exp_f32_e32 v67, v78
	v_mul_f32_e32 v64, v190, v64
	v_cmp_le_i32_e64 s[0:1], v65, v188
	v_add_u32_e32 v65, 0xffffff90, v13
	v_mul_f32_e32 v66, v190, v66
	v_cndmask_b32_e64 v64, 0, v64, s[0:1]
	v_cmp_le_i32_e64 s[0:1], v65, v188
	v_exp_f32_e32 v68, v79
	v_mul_f32_e32 v67, v190, v67
	v_cndmask_b32_e64 v65, 0, v66, s[0:1]
	v_add_u32_e32 v66, 0xffffffa0, v13
	v_cmp_le_i32_e64 s[0:1], v66, v188
	v_mul_f32_e32 v68, v190, v68
	v_add_f32_e32 v64, v64, v65
	v_cndmask_b32_e64 v66, 0, v67, s[0:1]
	v_add_u32_e32 v67, 0xffffffb0, v13
	v_cmp_le_i32_e64 s[0:1], v67, v188
	s_nop 1
	v_cndmask_b32_e64 v68, 0, v68, s[0:1]
	v_add_f32_e32 v65, v66, v68
	v_add_f32_e32 v64, v64, v65
	s_nop 1
	v_mov_b32_dpp v65, v64 quad_perm:[1,0,3,2] row_mask:0xf bank_mask:0xf
	v_add_f32_e32 v64, v64, v65
	s_nop 0
	s_nop 1
	v_mov_b32_dpp v66, v68 quad_perm:[1,0,3,2] row_mask:0xf bank_mask:0xf
	s_nop 1
	v_mov_b32_dpp v67, v64 quad_perm:[2,3,0,1] row_mask:0xf bank_mask:0xf
	v_add_f32_e32 v65, v68, v66
	s_nop 0
	s_nop 1
	v_mov_b32_dpp v66, v65 quad_perm:[2,3,0,1] row_mask:0xf bank_mask:0xf
	s_and_saveexec_b64 s[2:3], vcc
	s_cbranch_execz .LBB0_1596
	s_cmpk_gt_u32 s4, 0x7f
	s_cbranch_scc1 .LBB0_1594
	v_add_f32_e32 v64, v64, v67
	ds_add_f32 v12, v64 offset:24
.LBB0_1594:
	v_add_u32_e32 v64, 6, v14
	v_cmp_gt_u32_e64 s[0:1], s7, v64
	s_and_b64 exec, exec, s[0:1]
	s_cbranch_execz .LBB0_1596
	v_add_f32_e32 v64, v65, v66
	ds_add_f32 v12, v64 offset:28
.LBB0_1596:
	s_or_b64 exec, exec, s[2:3]
	ds_read_b128 v[80:83], v15 offset:4608
	ds_read_b128 v[84:87], v15 offset:4640
	v_cmp_le_i32_e64 s[0:1], v13, v188
	s_waitcnt lgkmcnt(1)
	v_mfma_f32_32x32x16_bf16 v[64:79], v[80:83], v[144:147], v[48:63]
	ds_read_b128 v[80:83], v15 offset:4672
	s_waitcnt lgkmcnt(1)
	v_mfma_f32_32x32x16_bf16 v[64:79], v[84:87], v[148:151], v[64:79]
	s_waitcnt lgkmcnt(0)
	v_mfma_f32_32x32x16_bf16 v[64:79], v[80:83], v[152:155], v[64:79]
	ds_read_b128 v[80:83], v15 offset:4704
	s_waitcnt lgkmcnt(0)
	v_mfma_f32_32x32x16_bf16 v[64:79], v[80:83], v[156:159], v[64:79]
	s_nop 11
	v_exp_f32_e32 v15, v64
	v_exp_f32_e32 v65, v65
	v_exp_f32_e32 v66, v66
	v_add_u32_e32 v64, 16, v13
	v_mul_f32_e32 v15, v190, v15
	v_cndmask_b32_e64 v15, 0, v15, s[0:1]
	v_mul_f32_e32 v65, v190, v65
	v_cmp_le_i32_e64 s[0:1], v64, v188
	v_exp_f32_e32 v67, v67
	v_mul_f32_e32 v66, v190, v66
	v_cndmask_b32_e64 v64, 0, v65, s[0:1]
	v_add_u32_e32 v65, 32, v13
	v_cmp_le_i32_e64 s[0:1], v65, v188
	v_mul_f32_e32 v67, v190, v67
	v_add_f32_e32 v15, v15, v64
	v_cndmask_b32_e64 v65, 0, v66, s[0:1]
	v_add_u32_e32 v66, 48, v13
	v_cmp_le_i32_e64 s[0:1], v66, v188
	s_nop 1
	v_cndmask_b32_e64 v66, 0, v67, s[0:1]
	v_add_f32_e32 v64, v65, v66
	v_add_f32_e32 v15, v15, v64
	s_nop 1
	v_mov_b32_dpp v64, v15 quad_perm:[1,0,3,2] row_mask:0xf bank_mask:0xf
	v_add_f32_e32 v15, v15, v64
	s_nop 0
	s_nop 1
	v_mov_b32_dpp v65, v66 quad_perm:[1,0,3,2] row_mask:0xf bank_mask:0xf
	v_add_f32_e32 v65, v66, v65
	s_nop 1
	v_mov_b32_dpp v64, v15 quad_perm:[2,3,0,1] row_mask:0xf bank_mask:0xf
	s_nop 1
	v_mov_b32_dpp v66, v65 quad_perm:[2,3,0,1] row_mask:0xf bank_mask:0xf
	s_and_saveexec_b64 s[2:3], vcc
	s_cbranch_execz .LBB0_1601
	s_cmpk_gt_u32 s4, 0x7f
	s_cbranch_scc1 .LBB0_1599
	v_add_f32_e32 v15, v15, v64
	ds_add_f32 v12, v15 offset:32
.LBB0_1599:
	v_add_u32_e32 v15, 8, v14
	v_cmp_gt_u32_e64 s[0:1], s7, v15
	s_and_b64 exec, exec, s[0:1]
	s_cbranch_execz .LBB0_1601
	v_add_f32_e32 v15, v65, v66
	ds_add_f32 v12, v15 offset:36
.LBB0_1601:
	s_or_b64 exec, exec, s[2:3]
	v_exp_f32_e32 v15, v68
	v_exp_f32_e32 v65, v69
	v_add_u32_e32 v64, 0x80, v13
	v_exp_f32_e32 v66, v70
	v_mul_f32_e32 v15, v190, v15
	v_cmp_le_i32_e64 s[0:1], v64, v188
	v_add_u32_e32 v64, 0x90, v13
	v_mul_f32_e32 v65, v190, v65
	v_cndmask_b32_e64 v15, 0, v15, s[0:1]
	v_cmp_le_i32_e64 s[0:1], v64, v188
	v_exp_f32_e32 v67, v71
	v_mul_f32_e32 v66, v190, v66
	v_cndmask_b32_e64 v64, 0, v65, s[0:1]
	v_add_u32_e32 v65, 0xa0, v13
	v_cmp_le_i32_e64 s[0:1], v65, v188
	v_mul_f32_e32 v67, v190, v67
	v_add_f32_e32 v15, v15, v64
	v_cndmask_b32_e64 v65, 0, v66, s[0:1]
	v_add_u32_e32 v66, 0xb0, v13
	v_cmp_le_i32_e64 s[0:1], v66, v188
	s_nop 1
	v_cndmask_b32_e64 v67, 0, v67, s[0:1]
	v_add_f32_e32 v64, v65, v67
	v_add_f32_e32 v15, v15, v64
	s_nop 1
	v_mov_b32_dpp v64, v15 quad_perm:[1,0,3,2] row_mask:0xf bank_mask:0xf
	v_add_f32_e32 v15, v15, v64
	s_nop 0
	s_nop 1
	v_mov_b32_dpp v65, v67 quad_perm:[1,0,3,2] row_mask:0xf bank_mask:0xf
	s_nop 1
	v_mov_b32_dpp v66, v15 quad_perm:[2,3,0,1] row_mask:0xf bank_mask:0xf
	v_add_f32_e32 v64, v67, v65
	s_nop 0
	s_nop 1
	v_mov_b32_dpp v65, v64 quad_perm:[2,3,0,1] row_mask:0xf bank_mask:0xf
	s_and_saveexec_b64 s[2:3], vcc
	s_cbranch_execz .LBB0_1606
	s_cmpk_gt_u32 s4, 0x7f
	s_cbranch_scc1 .LBB0_1604
	v_add_f32_e32 v15, v15, v66
	ds_add_f32 v12, v15 offset:40
.LBB0_1604:
	v_add_u32_e32 v15, 10, v14
	v_cmp_gt_u32_e64 s[0:1], s7, v15
	s_and_b64 exec, exec, s[0:1]
	s_cbranch_execz .LBB0_1606
	v_add_f32_e32 v15, v64, v65
	ds_add_f32 v12, v15 offset:44
.LBB0_1606:
	s_or_b64 exec, exec, s[2:3]
	v_exp_f32_e32 v15, v72
	v_exp_f32_e32 v65, v73
	v_add_u32_e32 v64, 0x100, v13
	v_exp_f32_e32 v66, v74
	v_mul_f32_e32 v15, v190, v15
	v_cmp_le_i32_e64 s[0:1], v64, v188
	v_add_u32_e32 v64, 0x110, v13
	v_mul_f32_e32 v65, v190, v65
	v_cndmask_b32_e64 v15, 0, v15, s[0:1]
	v_cmp_le_i32_e64 s[0:1], v64, v188
	v_exp_f32_e32 v67, v75
	v_mul_f32_e32 v66, v190, v66
	v_cndmask_b32_e64 v64, 0, v65, s[0:1]
	v_add_u32_e32 v65, 0x120, v13
	v_cmp_le_i32_e64 s[0:1], v65, v188
	v_mul_f32_e32 v67, v190, v67
	v_add_f32_e32 v15, v15, v64
	v_cndmask_b32_e64 v65, 0, v66, s[0:1]
	v_add_u32_e32 v66, 0x130, v13
	v_cmp_le_i32_e64 s[0:1], v66, v188
	s_nop 1
	v_cndmask_b32_e64 v67, 0, v67, s[0:1]
	v_add_f32_e32 v64, v65, v67
	v_add_f32_e32 v15, v15, v64
	s_nop 1
	v_mov_b32_dpp v64, v15 quad_perm:[1,0,3,2] row_mask:0xf bank_mask:0xf
	v_add_f32_e32 v15, v15, v64
	s_nop 0
	s_nop 1
	v_mov_b32_dpp v65, v67 quad_perm:[1,0,3,2] row_mask:0xf bank_mask:0xf
	s_nop 1
	v_mov_b32_dpp v66, v15 quad_perm:[2,3,0,1] row_mask:0xf bank_mask:0xf
	v_add_f32_e32 v64, v67, v65
	s_nop 0
	s_nop 1
	v_mov_b32_dpp v65, v64 quad_perm:[2,3,0,1] row_mask:0xf bank_mask:0xf
	s_and_saveexec_b64 s[2:3], vcc
	s_cbranch_execz .LBB0_1611
	s_cmpk_gt_u32 s4, 0x7f
	s_cbranch_scc1 .LBB0_1609
	v_add_f32_e32 v15, v15, v66
	ds_add_f32 v12, v15 offset:48
.LBB0_1609:
	v_add_u32_e32 v15, 12, v14
	v_cmp_gt_u32_e64 s[0:1], s7, v15
	s_and_b64 exec, exec, s[0:1]
	s_cbranch_execz .LBB0_1611
	v_add_f32_e32 v15, v64, v65
	ds_add_f32 v12, v15 offset:52
.LBB0_1611:
	s_or_b64 exec, exec, s[2:3]
	v_exp_f32_e32 v15, v76
	v_exp_f32_e32 v65, v77
	v_add_u32_e32 v64, 0x180, v13
	v_exp_f32_e32 v66, v78
	v_mul_f32_e32 v15, v190, v15
	v_cmp_le_i32_e64 s[0:1], v64, v188
	v_add_u32_e32 v64, 0x190, v13
	v_mul_f32_e32 v65, v190, v65
	v_cndmask_b32_e64 v15, 0, v15, s[0:1]
	v_cmp_le_i32_e64 s[0:1], v64, v188
	v_exp_f32_e32 v67, v79
	v_mul_f32_e32 v66, v190, v66
	v_cndmask_b32_e64 v64, 0, v65, s[0:1]
	v_add_u32_e32 v65, 0x1a0, v13
	v_cmp_le_i32_e64 s[0:1], v65, v188
	v_mul_f32_e32 v67, v190, v67
	v_add_f32_e32 v15, v15, v64
	v_cndmask_b32_e64 v65, 0, v66, s[0:1]
	v_add_u32_e32 v66, 0x1b0, v13
	v_cmp_le_i32_e64 s[0:1], v66, v188
	s_nop 1
	v_cndmask_b32_e64 v67, 0, v67, s[0:1]
	v_add_f32_e32 v64, v65, v67
	v_add_f32_e32 v15, v15, v64
	s_nop 1
	v_mov_b32_dpp v64, v15 quad_perm:[1,0,3,2] row_mask:0xf bank_mask:0xf
	v_add_f32_e32 v15, v15, v64
	s_nop 0
	s_nop 1
	v_mov_b32_dpp v65, v67 quad_perm:[1,0,3,2] row_mask:0xf bank_mask:0xf
	s_nop 1
	v_mov_b32_dpp v66, v15 quad_perm:[2,3,0,1] row_mask:0xf bank_mask:0xf
	v_add_f32_e32 v64, v67, v65
	s_nop 0
	s_nop 1
	v_mov_b32_dpp v65, v64 quad_perm:[2,3,0,1] row_mask:0xf bank_mask:0xf
	s_and_saveexec_b64 s[2:3], vcc
	s_cbranch_execz .LBB0_1573
	s_cmpk_gt_u32 s4, 0x7f
	s_cbranch_scc1 .LBB0_1614
	v_add_f32_e32 v15, v15, v66
	ds_add_f32 v12, v15 offset:56
.LBB0_1614:
	v_add_u32_e32 v14, 14, v14
	v_cmp_gt_u32_e64 s[0:1], s7, v14
	s_and_b64 exec, exec, s[0:1]
	s_cbranch_execz .LBB0_1573
	v_add_f32_e32 v14, v64, v65
	ds_add_f32 v12, v14 offset:60
	s_branch .LBB0_1573
